# GEMM K-loops: the four LDS-DMA pieces spread over both MFMA groups of the even half-step (one piece per 8 MFMAs)
# baseline (speedup 1.0000x reference)
.Lg1_ndw0:
.Lg1_swdw0:
	s_add_i32 s25, s25, 1
	v_add_u32_e32 v244, s28, v242
	v_add_u32_e32 v245, s28, v243
	ds_read_b128 v[198:201], v244 offset:0
	ds_read_b128 v[202:205], v244 offset:2048
	ds_read_b128 v[210:213], v244 offset:4096
	ds_read_b128 v[214:217], v244 offset:6144
	ds_read_b128 v[218:221], v244 offset:8192
	ds_read_b128 v[222:225], v244 offset:10240
	ds_read_b128 v[226:229], v244 offset:12288
	ds_read_b128 v[230:233], v244 offset:14336
	s_waitcnt lgkmcnt(4)
	s_add_i32 m0, s27, s97
	v_mfma_f32_16x16x32_bf16 v[0:3], v[128:131], v[198:201], v[0:3]
	v_mfma_f32_16x16x32_bf16 v[32:35], v[132:135], v[198:201], v[32:35]
	v_mfma_f32_16x16x32_bf16 v[64:67], v[136:139], v[198:201], v[64:67]
	v_mfma_f32_16x16x32_bf16 v[96:99], v[140:143], v[198:201], v[96:99]
	v_mfma_f32_16x16x32_bf16 v[4:7], v[128:131], v[202:205], v[4:7]
	v_mfma_f32_16x16x32_bf16 v[36:39], v[132:135], v[202:205], v[36:39]
	v_mfma_f32_16x16x32_bf16 v[68:71], v[136:139], v[202:205], v[68:71]
	v_mfma_f32_16x16x32_bf16 v[100:103], v[140:143], v[202:205], v[100:103]
	global_load_lds_dwordx4 v234, s[58:59]
	s_add_i32 m0, m0, 0x400
	v_mfma_f32_16x16x32_bf16 v[8:11], v[128:131], v[210:213], v[8:11]
	v_mfma_f32_16x16x32_bf16 v[40:43], v[132:135], v[210:213], v[40:43]
	v_mfma_f32_16x16x32_bf16 v[72:75], v[136:139], v[210:213], v[72:75]
	v_mfma_f32_16x16x32_bf16 v[104:107], v[140:143], v[210:213], v[104:107]
	v_mfma_f32_16x16x32_bf16 v[12:15], v[128:131], v[214:217], v[12:15]
	v_mfma_f32_16x16x32_bf16 v[44:47], v[132:135], v[214:217], v[44:47]
	v_mfma_f32_16x16x32_bf16 v[76:79], v[136:139], v[214:217], v[76:79]
	v_mfma_f32_16x16x32_bf16 v[108:111], v[140:143], v[214:217], v[108:111]
	global_load_lds_dwordx4 v235, s[58:59]
	s_add_i32 m0, m0, 0x400
	ds_read_b128 v[198:201], v245 offset:0
	ds_read_b128 v[202:205], v245 offset:2048
	ds_read_b128 v[210:213], v245 offset:4096
	ds_read_b128 v[214:217], v245 offset:6144
	s_waitcnt lgkmcnt(4)
	v_mfma_f32_16x16x32_bf16 v[16:19], v[128:131], v[218:221], v[16:19]
	v_mfma_f32_16x16x32_bf16 v[48:51], v[132:135], v[218:221], v[48:51]
	v_mfma_f32_16x16x32_bf16 v[80:83], v[136:139], v[218:221], v[80:83]
	v_mfma_f32_16x16x32_bf16 v[112:115], v[140:143], v[218:221], v[112:115]
	v_mfma_f32_16x16x32_bf16 v[20:23], v[128:131], v[222:225], v[20:23]
	v_mfma_f32_16x16x32_bf16 v[52:55], v[132:135], v[222:225], v[52:55]
	v_mfma_f32_16x16x32_bf16 v[84:87], v[136:139], v[222:225], v[84:87]
	v_mfma_f32_16x16x32_bf16 v[116:119], v[140:143], v[222:225], v[116:119]
	global_load_lds_dwordx4 v236, s[58:59]
	s_add_i32 m0, m0, 0x400
	v_mfma_f32_16x16x32_bf16 v[24:27], v[128:131], v[226:229], v[24:27]
	v_mfma_f32_16x16x32_bf16 v[56:59], v[132:135], v[226:229], v[56:59]
	v_mfma_f32_16x16x32_bf16 v[88:91], v[136:139], v[226:229], v[88:91]
	v_mfma_f32_16x16x32_bf16 v[120:123], v[140:143], v[226:229], v[120:123]
	v_mfma_f32_16x16x32_bf16 v[28:31], v[128:131], v[230:233], v[28:31]
	v_mfma_f32_16x16x32_bf16 v[60:63], v[132:135], v[230:233], v[60:63]
	v_mfma_f32_16x16x32_bf16 v[92:95], v[136:139], v[230:233], v[92:95]
	v_mfma_f32_16x16x32_bf16 v[124:127], v[140:143], v[230:233], v[124:127]
	global_load_lds_dwordx4 v237, s[58:59]
	s_cmp_eq_u32 s29, 13
	s_cbranch_scc1 .Lg1_saa1
	s_add_u32 s58, s58, 128
	s_addc_u32 s59, s59, 0
	s_branch .Lg1_sada1

.Lg1_nda1:
.Lg1_sada1:
	ds_read_b128 v[218:221], v245 offset:8192
	ds_read_b128 v[222:225], v245 offset:10240
	ds_read_b128 v[226:229], v245 offset:12288
	ds_read_b128 v[230:233], v245 offset:14336
	s_waitcnt vmcnt(16)
	global_load_dwordx4 v[128:131], v238, s[56:57]
	global_load_dwordx4 v[132:135], v239, s[56:57]
	global_load_dwordx4 v[136:139], v240, s[56:57]
	global_load_dwordx4 v[140:143], v241, s[56:57]
	s_cmp_eq_u32 s25, 31
	s_cbranch_scc1 .Lg1_sww2
	s_add_u32 s56, s56, 1024
	s_addc_u32 s57, s57, 0
	s_branch .Lg1_swdw2

.Lg1_ndw3:
.Lg1_swdw3:
	s_add_i32 s25, s25, 1
	v_add_u32_e32 v244, s28, v242
	v_add_u32_e32 v245, s28, v243
	ds_read_b128 v[198:201], v244 offset:0
	ds_read_b128 v[202:205], v244 offset:2048
	ds_read_b128 v[210:213], v244 offset:4096
	ds_read_b128 v[214:217], v244 offset:6144
	ds_read_b128 v[218:221], v244 offset:8192
	ds_read_b128 v[222:225], v244 offset:10240
	ds_read_b128 v[226:229], v244 offset:12288
	ds_read_b128 v[230:233], v244 offset:14336
	s_waitcnt lgkmcnt(4)
	s_add_i32 m0, s27, s97
	v_mfma_f32_16x16x32_bf16 v[0:3], v[160:163], v[198:201], v[0:3]
	v_mfma_f32_16x16x32_bf16 v[32:35], v[164:167], v[198:201], v[32:35]
	v_mfma_f32_16x16x32_bf16 v[64:67], v[168:171], v[198:201], v[64:67]
	v_mfma_f32_16x16x32_bf16 v[96:99], v[172:175], v[198:201], v[96:99]
	v_mfma_f32_16x16x32_bf16 v[4:7], v[160:163], v[202:205], v[4:7]
	v_mfma_f32_16x16x32_bf16 v[36:39], v[164:167], v[202:205], v[36:39]
	v_mfma_f32_16x16x32_bf16 v[68:71], v[168:171], v[202:205], v[68:71]
	v_mfma_f32_16x16x32_bf16 v[100:103], v[172:175], v[202:205], v[100:103]
	global_load_lds_dwordx4 v234, s[58:59]
	s_add_i32 m0, m0, 0x400
	v_mfma_f32_16x16x32_bf16 v[8:11], v[160:163], v[210:213], v[8:11]
	v_mfma_f32_16x16x32_bf16 v[40:43], v[164:167], v[210:213], v[40:43]
	v_mfma_f32_16x16x32_bf16 v[72:75], v[168:171], v[210:213], v[72:75]
	v_mfma_f32_16x16x32_bf16 v[104:107], v[172:175], v[210:213], v[104:107]
	v_mfma_f32_16x16x32_bf16 v[12:15], v[160:163], v[214:217], v[12:15]
	v_mfma_f32_16x16x32_bf16 v[44:47], v[164:167], v[214:217], v[44:47]
	v_mfma_f32_16x16x32_bf16 v[76:79], v[168:171], v[214:217], v[76:79]
	v_mfma_f32_16x16x32_bf16 v[108:111], v[172:175], v[214:217], v[108:111]
	global_load_lds_dwordx4 v235, s[58:59]
	s_add_i32 m0, m0, 0x400
	ds_read_b128 v[198:201], v245 offset:0
	ds_read_b128 v[202:205], v245 offset:2048
	ds_read_b128 v[210:213], v245 offset:4096
	ds_read_b128 v[214:217], v245 offset:6144
	s_waitcnt lgkmcnt(4)
	v_mfma_f32_16x16x32_bf16 v[16:19], v[160:163], v[218:221], v[16:19]
	v_mfma_f32_16x16x32_bf16 v[48:51], v[164:167], v[218:221], v[48:51]
	v_mfma_f32_16x16x32_bf16 v[80:83], v[168:171], v[218:221], v[80:83]
	v_mfma_f32_16x16x32_bf16 v[112:115], v[172:175], v[218:221], v[112:115]
	v_mfma_f32_16x16x32_bf16 v[20:23], v[160:163], v[222:225], v[20:23]
	v_mfma_f32_16x16x32_bf16 v[52:55], v[164:167], v[222:225], v[52:55]
	v_mfma_f32_16x16x32_bf16 v[84:87], v[168:171], v[222:225], v[84:87]
	v_mfma_f32_16x16x32_bf16 v[116:119], v[172:175], v[222:225], v[116:119]
	global_load_lds_dwordx4 v236, s[58:59]
	s_add_i32 m0, m0, 0x400
	v_mfma_f32_16x16x32_bf16 v[24:27], v[160:163], v[226:229], v[24:27]
	v_mfma_f32_16x16x32_bf16 v[56:59], v[164:167], v[226:229], v[56:59]
	v_mfma_f32_16x16x32_bf16 v[88:91], v[168:171], v[226:229], v[88:91]
	v_mfma_f32_16x16x32_bf16 v[120:123], v[172:175], v[226:229], v[120:123]
	v_mfma_f32_16x16x32_bf16 v[28:31], v[160:163], v[230:233], v[28:31]
	v_mfma_f32_16x16x32_bf16 v[60:63], v[164:167], v[230:233], v[60:63]
	v_mfma_f32_16x16x32_bf16 v[92:95], v[168:171], v[230:233], v[92:95]
	v_mfma_f32_16x16x32_bf16 v[124:127], v[172:175], v[230:233], v[124:127]
	global_load_lds_dwordx4 v237, s[58:59]
	s_cmp_eq_u32 s29, 13
	s_cbranch_scc1 .Lg1_saa4
	s_add_u32 s58, s58, 128
	s_addc_u32 s59, s59, 0
	s_branch .Lg1_sada4

.Lg1_nda4:
.Lg1_sada4:
	ds_read_b128 v[218:221], v245 offset:8192
	ds_read_b128 v[222:225], v245 offset:10240
	ds_read_b128 v[226:229], v245 offset:12288
	ds_read_b128 v[230:233], v245 offset:14336
	s_waitcnt vmcnt(16)
	global_load_dwordx4 v[160:163], v238, s[56:57]
	global_load_dwordx4 v[164:167], v239, s[56:57]
	global_load_dwordx4 v[168:171], v240, s[56:57]
	global_load_dwordx4 v[172:175], v241, s[56:57]
	s_cmp_eq_u32 s25, 31
	s_cbranch_scc1 .Lg1_sww5
	s_add_u32 s56, s56, 1024
	s_addc_u32 s57, s57, 0
	s_branch .Lg1_swdw5

.Lg2_wndw0:
.Lg2_swdw0:
	s_add_i32 s59, s59, 1
	v_add_u32_e32 v244, s56, v242
	v_add_u32_e32 v245, s56, v243
	ds_read_b128 v[200:203], v244 offset:0
	ds_read_b128 v[204:207], v244 offset:2048
	ds_read_b128 v[210:213], v244 offset:4096
	ds_read_b128 v[214:217], v244 offset:6144
	ds_read_b128 v[218:221], v244 offset:8192
	ds_read_b128 v[222:225], v244 offset:10240
	ds_read_b128 v[226:229], v244 offset:12288
	ds_read_b128 v[230:233], v244 offset:14336
	s_waitcnt lgkmcnt(4)
	s_add_i32 m0, s57, s60
	v_mfma_f32_16x16x32_bf16 v[0:3], v[128:131], v[200:203], v[0:3]
	v_mfma_f32_16x16x32_bf16 v[32:35], v[132:135], v[200:203], v[32:35]
	v_mfma_f32_16x16x32_bf16 v[64:67], v[136:139], v[200:203], v[64:67]
	v_mfma_f32_16x16x32_bf16 v[96:99], v[140:143], v[200:203], v[96:99]
	v_mfma_f32_16x16x32_bf16 v[4:7], v[128:131], v[204:207], v[4:7]
	v_mfma_f32_16x16x32_bf16 v[36:39], v[132:135], v[204:207], v[36:39]
	v_mfma_f32_16x16x32_bf16 v[68:71], v[136:139], v[204:207], v[68:71]
	v_mfma_f32_16x16x32_bf16 v[100:103], v[140:143], v[204:207], v[100:103]
	global_load_lds_dwordx4 v234, s[52:53]
	s_add_i32 m0, m0, 0x400
	v_mfma_f32_16x16x32_bf16 v[8:11], v[128:131], v[210:213], v[8:11]
	v_mfma_f32_16x16x32_bf16 v[40:43], v[132:135], v[210:213], v[40:43]
	v_mfma_f32_16x16x32_bf16 v[72:75], v[136:139], v[210:213], v[72:75]
	v_mfma_f32_16x16x32_bf16 v[104:107], v[140:143], v[210:213], v[104:107]
	v_mfma_f32_16x16x32_bf16 v[12:15], v[128:131], v[214:217], v[12:15]
	v_mfma_f32_16x16x32_bf16 v[44:47], v[132:135], v[214:217], v[44:47]
	v_mfma_f32_16x16x32_bf16 v[76:79], v[136:139], v[214:217], v[76:79]
	v_mfma_f32_16x16x32_bf16 v[108:111], v[140:143], v[214:217], v[108:111]
	global_load_lds_dwordx4 v235, s[52:53]
	s_add_i32 m0, m0, 0x400
	ds_read_b128 v[200:203], v245 offset:0
	ds_read_b128 v[204:207], v245 offset:2048
	ds_read_b128 v[210:213], v245 offset:4096
	ds_read_b128 v[214:217], v245 offset:6144
	s_waitcnt lgkmcnt(4)
	v_mfma_f32_16x16x32_bf16 v[16:19], v[128:131], v[218:221], v[16:19]
	v_mfma_f32_16x16x32_bf16 v[48:51], v[132:135], v[218:221], v[48:51]
	v_mfma_f32_16x16x32_bf16 v[80:83], v[136:139], v[218:221], v[80:83]
	v_mfma_f32_16x16x32_bf16 v[112:115], v[140:143], v[218:221], v[112:115]
	v_mfma_f32_16x16x32_bf16 v[20:23], v[128:131], v[222:225], v[20:23]
	v_mfma_f32_16x16x32_bf16 v[52:55], v[132:135], v[222:225], v[52:55]
	v_mfma_f32_16x16x32_bf16 v[84:87], v[136:139], v[222:225], v[84:87]
	v_mfma_f32_16x16x32_bf16 v[116:119], v[140:143], v[222:225], v[116:119]
	global_load_lds_dwordx4 v236, s[52:53]
	s_add_i32 m0, m0, 0x400
	v_mfma_f32_16x16x32_bf16 v[24:27], v[128:131], v[226:229], v[24:27]
	v_mfma_f32_16x16x32_bf16 v[56:59], v[132:135], v[226:229], v[56:59]
	v_mfma_f32_16x16x32_bf16 v[88:91], v[136:139], v[226:229], v[88:91]
	v_mfma_f32_16x16x32_bf16 v[120:123], v[140:143], v[226:229], v[120:123]
	v_mfma_f32_16x16x32_bf16 v[28:31], v[128:131], v[230:233], v[28:31]
	v_mfma_f32_16x16x32_bf16 v[60:63], v[132:135], v[230:233], v[60:63]
	v_mfma_f32_16x16x32_bf16 v[92:95], v[136:139], v[230:233], v[92:95]
	v_mfma_f32_16x16x32_bf16 v[124:127], v[140:143], v[230:233], v[124:127]
	global_load_lds_dwordx4 v237, s[52:53]
	s_cmp_eq_u32 s58, 13
	s_cbranch_scc1 .Lg2_saa1
	s_add_u32 s52, s52, 128
	s_addc_u32 s53, s53, 0
	s_branch .Lg2_sada1

.Lg2_nda1:
.Lg2_sada1:
	ds_read_b128 v[218:221], v245 offset:8192
	ds_read_b128 v[222:225], v245 offset:10240
	ds_read_b128 v[226:229], v245 offset:12288
	ds_read_b128 v[230:233], v245 offset:14336
	s_waitcnt vmcnt(16)
	global_load_dwordx4 v[128:131], v238, s[54:55]
	global_load_dwordx4 v[132:135], v239, s[54:55]
	global_load_dwordx4 v[136:139], v240, s[54:55]
	global_load_dwordx4 v[140:143], v241, s[54:55]
	s_cmp_eq_u32 s59, 31
	s_cbranch_scc1 .Lg2_sww2
	s_add_u32 s54, s54, 1024
	s_addc_u32 s55, s55, 0
	s_branch .Lg2_swdw2

.Lg2_wndw3:
.Lg2_swdw3:
	s_add_i32 s59, s59, 1
	v_add_u32_e32 v244, s56, v242
	v_add_u32_e32 v245, s56, v243
	ds_read_b128 v[200:203], v244 offset:0
	ds_read_b128 v[204:207], v244 offset:2048
	ds_read_b128 v[210:213], v244 offset:4096
	ds_read_b128 v[214:217], v244 offset:6144
	ds_read_b128 v[218:221], v244 offset:8192
	ds_read_b128 v[222:225], v244 offset:10240
	ds_read_b128 v[226:229], v244 offset:12288
	ds_read_b128 v[230:233], v244 offset:14336
	s_waitcnt lgkmcnt(4)
	s_add_i32 m0, s57, s60
	v_mfma_f32_16x16x32_bf16 v[0:3], v[160:163], v[200:203], v[0:3]
	v_mfma_f32_16x16x32_bf16 v[32:35], v[164:167], v[200:203], v[32:35]
	v_mfma_f32_16x16x32_bf16 v[64:67], v[168:171], v[200:203], v[64:67]
	v_mfma_f32_16x16x32_bf16 v[96:99], v[172:175], v[200:203], v[96:99]
	v_mfma_f32_16x16x32_bf16 v[4:7], v[160:163], v[204:207], v[4:7]
	v_mfma_f32_16x16x32_bf16 v[36:39], v[164:167], v[204:207], v[36:39]
	v_mfma_f32_16x16x32_bf16 v[68:71], v[168:171], v[204:207], v[68:71]
	v_mfma_f32_16x16x32_bf16 v[100:103], v[172:175], v[204:207], v[100:103]
	global_load_lds_dwordx4 v234, s[52:53]
	s_add_i32 m0, m0, 0x400
	v_mfma_f32_16x16x32_bf16 v[8:11], v[160:163], v[210:213], v[8:11]
	v_mfma_f32_16x16x32_bf16 v[40:43], v[164:167], v[210:213], v[40:43]
	v_mfma_f32_16x16x32_bf16 v[72:75], v[168:171], v[210:213], v[72:75]
	v_mfma_f32_16x16x32_bf16 v[104:107], v[172:175], v[210:213], v[104:107]
	v_mfma_f32_16x16x32_bf16 v[12:15], v[160:163], v[214:217], v[12:15]
	v_mfma_f32_16x16x32_bf16 v[44:47], v[164:167], v[214:217], v[44:47]
	v_mfma_f32_16x16x32_bf16 v[76:79], v[168:171], v[214:217], v[76:79]
	v_mfma_f32_16x16x32_bf16 v[108:111], v[172:175], v[214:217], v[108:111]
	global_load_lds_dwordx4 v235, s[52:53]
	s_add_i32 m0, m0, 0x400
	ds_read_b128 v[200:203], v245 offset:0
	ds_read_b128 v[204:207], v245 offset:2048
	ds_read_b128 v[210:213], v245 offset:4096
	ds_read_b128 v[214:217], v245 offset:6144
	s_waitcnt lgkmcnt(4)
	v_mfma_f32_16x16x32_bf16 v[16:19], v[160:163], v[218:221], v[16:19]
	v_mfma_f32_16x16x32_bf16 v[48:51], v[164:167], v[218:221], v[48:51]
	v_mfma_f32_16x16x32_bf16 v[80:83], v[168:171], v[218:221], v[80:83]
	v_mfma_f32_16x16x32_bf16 v[112:115], v[172:175], v[218:221], v[112:115]
	v_mfma_f32_16x16x32_bf16 v[20:23], v[160:163], v[222:225], v[20:23]
	v_mfma_f32_16x16x32_bf16 v[52:55], v[164:167], v[222:225], v[52:55]
	v_mfma_f32_16x16x32_bf16 v[84:87], v[168:171], v[222:225], v[84:87]
	v_mfma_f32_16x16x32_bf16 v[116:119], v[172:175], v[222:225], v[116:119]
	global_load_lds_dwordx4 v236, s[52:53]
	s_add_i32 m0, m0, 0x400
	v_mfma_f32_16x16x32_bf16 v[24:27], v[160:163], v[226:229], v[24:27]
	v_mfma_f32_16x16x32_bf16 v[56:59], v[164:167], v[226:229], v[56:59]
	v_mfma_f32_16x16x32_bf16 v[88:91], v[168:171], v[226:229], v[88:91]
	v_mfma_f32_16x16x32_bf16 v[120:123], v[172:175], v[226:229], v[120:123]
	v_mfma_f32_16x16x32_bf16 v[28:31], v[160:163], v[230:233], v[28:31]
	v_mfma_f32_16x16x32_bf16 v[60:63], v[164:167], v[230:233], v[60:63]
	v_mfma_f32_16x16x32_bf16 v[92:95], v[168:171], v[230:233], v[92:95]
	v_mfma_f32_16x16x32_bf16 v[124:127], v[172:175], v[230:233], v[124:127]
	global_load_lds_dwordx4 v237, s[52:53]
	s_cmp_eq_u32 s58, 13
	s_cbranch_scc1 .Lg2_saa4
	s_add_u32 s52, s52, 128
	s_addc_u32 s53, s53, 0
	s_branch .Lg2_sada4

.Lg2_nda4:
.Lg2_sada4:
	ds_read_b128 v[218:221], v245 offset:8192
	ds_read_b128 v[222:225], v245 offset:10240
	ds_read_b128 v[226:229], v245 offset:12288
	ds_read_b128 v[230:233], v245 offset:14336
	s_waitcnt vmcnt(16)
	global_load_dwordx4 v[160:163], v238, s[54:55]
	global_load_dwordx4 v[164:167], v239, s[54:55]
	global_load_dwordx4 v[168:171], v240, s[54:55]
	global_load_dwordx4 v[172:175], v241, s[54:55]
	s_cmp_eq_u32 s59, 31
	s_cbranch_scc1 .Lg2_sww5
	s_add_u32 s54, s54, 1024
	s_addc_u32 s55, s55, 0
	s_branch .Lg2_swdw5

.Lg3_wndw0:
.Lg3_swdw0:
	s_add_i32 s19, s19, 1
	v_add_u32_e32 v244, s16, v242
	v_add_u32_e32 v245, s16, v243
	ds_read_b128 v[198:201], v244 offset:0
	ds_read_b128 v[202:205], v244 offset:2048
	ds_read_b128 v[210:213], v244 offset:4096
	ds_read_b128 v[214:217], v244 offset:6144
	ds_read_b128 v[218:221], v244 offset:8192
	ds_read_b128 v[222:225], v244 offset:10240
	ds_read_b128 v[226:229], v244 offset:12288
	ds_read_b128 v[230:233], v244 offset:14336
	s_waitcnt lgkmcnt(4)
	s_add_i32 m0, s17, s20
	v_mfma_f32_16x16x32_bf16 v[0:3], v[128:131], v[198:201], v[0:3]
	v_mfma_f32_16x16x32_bf16 v[32:35], v[132:135], v[198:201], v[32:35]
	v_mfma_f32_16x16x32_bf16 v[64:67], v[136:139], v[198:201], v[64:67]
	v_mfma_f32_16x16x32_bf16 v[96:99], v[140:143], v[198:201], v[96:99]
	v_mfma_f32_16x16x32_bf16 v[4:7], v[128:131], v[202:205], v[4:7]
	v_mfma_f32_16x16x32_bf16 v[36:39], v[132:135], v[202:205], v[36:39]
	v_mfma_f32_16x16x32_bf16 v[68:71], v[136:139], v[202:205], v[68:71]
	v_mfma_f32_16x16x32_bf16 v[100:103], v[140:143], v[202:205], v[100:103]
	global_load_lds_dwordx4 v234, s[12:13]
	s_add_i32 m0, m0, 0x400
	v_mfma_f32_16x16x32_bf16 v[8:11], v[128:131], v[210:213], v[8:11]
	v_mfma_f32_16x16x32_bf16 v[40:43], v[132:135], v[210:213], v[40:43]
	v_mfma_f32_16x16x32_bf16 v[72:75], v[136:139], v[210:213], v[72:75]
	v_mfma_f32_16x16x32_bf16 v[104:107], v[140:143], v[210:213], v[104:107]
	v_mfma_f32_16x16x32_bf16 v[12:15], v[128:131], v[214:217], v[12:15]
	v_mfma_f32_16x16x32_bf16 v[44:47], v[132:135], v[214:217], v[44:47]
	v_mfma_f32_16x16x32_bf16 v[76:79], v[136:139], v[214:217], v[76:79]
	v_mfma_f32_16x16x32_bf16 v[108:111], v[140:143], v[214:217], v[108:111]
	global_load_lds_dwordx4 v235, s[12:13]
	s_add_i32 m0, m0, 0x400
	ds_read_b128 v[198:201], v245 offset:0
	ds_read_b128 v[202:205], v245 offset:2048
	ds_read_b128 v[210:213], v245 offset:4096
	ds_read_b128 v[214:217], v245 offset:6144
	s_waitcnt lgkmcnt(4)
	v_mfma_f32_16x16x32_bf16 v[16:19], v[128:131], v[218:221], v[16:19]
	v_mfma_f32_16x16x32_bf16 v[48:51], v[132:135], v[218:221], v[48:51]
	v_mfma_f32_16x16x32_bf16 v[80:83], v[136:139], v[218:221], v[80:83]
	v_mfma_f32_16x16x32_bf16 v[112:115], v[140:143], v[218:221], v[112:115]
	v_mfma_f32_16x16x32_bf16 v[20:23], v[128:131], v[222:225], v[20:23]
	v_mfma_f32_16x16x32_bf16 v[52:55], v[132:135], v[222:225], v[52:55]
	v_mfma_f32_16x16x32_bf16 v[84:87], v[136:139], v[222:225], v[84:87]
	v_mfma_f32_16x16x32_bf16 v[116:119], v[140:143], v[222:225], v[116:119]
	global_load_lds_dwordx4 v236, s[12:13]
	s_add_i32 m0, m0, 0x400
	v_mfma_f32_16x16x32_bf16 v[24:27], v[128:131], v[226:229], v[24:27]
	v_mfma_f32_16x16x32_bf16 v[56:59], v[132:135], v[226:229], v[56:59]
	v_mfma_f32_16x16x32_bf16 v[88:91], v[136:139], v[226:229], v[88:91]
	v_mfma_f32_16x16x32_bf16 v[120:123], v[140:143], v[226:229], v[120:123]
	v_mfma_f32_16x16x32_bf16 v[28:31], v[128:131], v[230:233], v[28:31]
	v_mfma_f32_16x16x32_bf16 v[60:63], v[132:135], v[230:233], v[60:63]
	v_mfma_f32_16x16x32_bf16 v[92:95], v[136:139], v[230:233], v[92:95]
	v_mfma_f32_16x16x32_bf16 v[124:127], v[140:143], v[230:233], v[124:127]
	global_load_lds_dwordx4 v237, s[12:13]
	s_cmp_eq_u32 s18, 13
	s_cbranch_scc1 .Lg3_saa1
	s_add_u32 s12, s12, 128
	s_addc_u32 s13, s13, 0
	s_branch .Lg3_sada1

.Lg3_nda1:
.Lg3_sada1:
	ds_read_b128 v[218:221], v245 offset:8192
	ds_read_b128 v[222:225], v245 offset:10240
	ds_read_b128 v[226:229], v245 offset:12288
	ds_read_b128 v[230:233], v245 offset:14336
	s_waitcnt vmcnt(16)
	global_load_dwordx4 v[128:131], v238, s[14:15]
	global_load_dwordx4 v[132:135], v239, s[14:15]
	global_load_dwordx4 v[136:139], v240, s[14:15]
	global_load_dwordx4 v[140:143], v241, s[14:15]
	s_cmp_eq_u32 s19, 31
	s_cbranch_scc1 .Lg3_sww2
	s_add_u32 s14, s14, 1024
	s_addc_u32 s15, s15, 0
	s_branch .Lg3_swdw2

.Lg3_wndw3:
.Lg3_swdw3:
	s_add_i32 s19, s19, 1
	v_add_u32_e32 v244, s16, v242
	v_add_u32_e32 v245, s16, v243
	ds_read_b128 v[198:201], v244 offset:0
	ds_read_b128 v[202:205], v244 offset:2048
	ds_read_b128 v[210:213], v244 offset:4096
	ds_read_b128 v[214:217], v244 offset:6144
	ds_read_b128 v[218:221], v244 offset:8192
	ds_read_b128 v[222:225], v244 offset:10240
	ds_read_b128 v[226:229], v244 offset:12288
	ds_read_b128 v[230:233], v244 offset:14336
	s_waitcnt lgkmcnt(4)
	s_add_i32 m0, s17, s20
	v_mfma_f32_16x16x32_bf16 v[0:3], v[160:163], v[198:201], v[0:3]
	v_mfma_f32_16x16x32_bf16 v[32:35], v[164:167], v[198:201], v[32:35]
	v_mfma_f32_16x16x32_bf16 v[64:67], v[168:171], v[198:201], v[64:67]
	v_mfma_f32_16x16x32_bf16 v[96:99], v[172:175], v[198:201], v[96:99]
	v_mfma_f32_16x16x32_bf16 v[4:7], v[160:163], v[202:205], v[4:7]
	v_mfma_f32_16x16x32_bf16 v[36:39], v[164:167], v[202:205], v[36:39]
	v_mfma_f32_16x16x32_bf16 v[68:71], v[168:171], v[202:205], v[68:71]
	v_mfma_f32_16x16x32_bf16 v[100:103], v[172:175], v[202:205], v[100:103]
	global_load_lds_dwordx4 v234, s[12:13]
	s_add_i32 m0, m0, 0x400
	v_mfma_f32_16x16x32_bf16 v[8:11], v[160:163], v[210:213], v[8:11]
	v_mfma_f32_16x16x32_bf16 v[40:43], v[164:167], v[210:213], v[40:43]
	v_mfma_f32_16x16x32_bf16 v[72:75], v[168:171], v[210:213], v[72:75]
	v_mfma_f32_16x16x32_bf16 v[104:107], v[172:175], v[210:213], v[104:107]
	v_mfma_f32_16x16x32_bf16 v[12:15], v[160:163], v[214:217], v[12:15]
	v_mfma_f32_16x16x32_bf16 v[44:47], v[164:167], v[214:217], v[44:47]
	v_mfma_f32_16x16x32_bf16 v[76:79], v[168:171], v[214:217], v[76:79]
	v_mfma_f32_16x16x32_bf16 v[108:111], v[172:175], v[214:217], v[108:111]
	global_load_lds_dwordx4 v235, s[12:13]
	s_add_i32 m0, m0, 0x400
	ds_read_b128 v[198:201], v245 offset:0
	ds_read_b128 v[202:205], v245 offset:2048
	ds_read_b128 v[210:213], v245 offset:4096
	ds_read_b128 v[214:217], v245 offset:6144
	s_waitcnt lgkmcnt(4)
	v_mfma_f32_16x16x32_bf16 v[16:19], v[160:163], v[218:221], v[16:19]
	v_mfma_f32_16x16x32_bf16 v[48:51], v[164:167], v[218:221], v[48:51]
	v_mfma_f32_16x16x32_bf16 v[80:83], v[168:171], v[218:221], v[80:83]
	v_mfma_f32_16x16x32_bf16 v[112:115], v[172:175], v[218:221], v[112:115]
	v_mfma_f32_16x16x32_bf16 v[20:23], v[160:163], v[222:225], v[20:23]
	v_mfma_f32_16x16x32_bf16 v[52:55], v[164:167], v[222:225], v[52:55]
	v_mfma_f32_16x16x32_bf16 v[84:87], v[168:171], v[222:225], v[84:87]
	v_mfma_f32_16x16x32_bf16 v[116:119], v[172:175], v[222:225], v[116:119]
	global_load_lds_dwordx4 v236, s[12:13]
	s_add_i32 m0, m0, 0x400
	v_mfma_f32_16x16x32_bf16 v[24:27], v[160:163], v[226:229], v[24:27]
	v_mfma_f32_16x16x32_bf16 v[56:59], v[164:167], v[226:229], v[56:59]
	v_mfma_f32_16x16x32_bf16 v[88:91], v[168:171], v[226:229], v[88:91]
	v_mfma_f32_16x16x32_bf16 v[120:123], v[172:175], v[226:229], v[120:123]
	v_mfma_f32_16x16x32_bf16 v[28:31], v[160:163], v[230:233], v[28:31]
	v_mfma_f32_16x16x32_bf16 v[60:63], v[164:167], v[230:233], v[60:63]
	v_mfma_f32_16x16x32_bf16 v[92:95], v[168:171], v[230:233], v[92:95]
	v_mfma_f32_16x16x32_bf16 v[124:127], v[172:175], v[230:233], v[124:127]
	global_load_lds_dwordx4 v237, s[12:13]
	s_cmp_eq_u32 s18, 13
	s_cbranch_scc1 .Lg3_saa4
	s_add_u32 s12, s12, 128
	s_addc_u32 s13, s13, 0
	s_branch .Lg3_sada4

.Lg3_nda4:
.Lg3_sada4:
	ds_read_b128 v[218:221], v245 offset:8192
	ds_read_b128 v[222:225], v245 offset:10240
	ds_read_b128 v[226:229], v245 offset:12288
	ds_read_b128 v[230:233], v245 offset:14336
	s_waitcnt vmcnt(16)
	global_load_dwordx4 v[160:163], v238, s[14:15]
	global_load_dwordx4 v[164:167], v239, s[14:15]
	global_load_dwordx4 v[168:171], v240, s[14:15]
	global_load_dwordx4 v[172:175], v241, s[14:15]
	s_cmp_eq_u32 s19, 31
	s_cbranch_scc1 .Lg3_sww5
	s_add_u32 s14, s14, 1024
	s_addc_u32 s15, s15, 0
	s_branch .Lg3_swdw5
